# grid barrier: the first workgroup of each XCD to arrive starts the L2 write-back early (6 sites)
# speedup vs baseline: 1.0097x; 1.0097x over previous
; DI unsigned xb_ld(unsigned* p)              { return __hip_atomic_load(p, __ATOMIC_RELAXED, __HIP_MEMORY_SCOPE_AGENT); }
; DI unsigned xb_add(unsigned* p, unsigned v) { return __hip_atomic_fetch_add(p, v, __ATOMIC_RELAXED, __HIP_MEMORY_SCOPE_AGENT); }
; #define XB_SPIN(cond, bar) do { unsigned _sp = 0; while (cond) { __builtin_amdgcn_s_sleep(1); \
;     if ((++_sp & 255u) == 0u) { if (xb_ld(&(bar)[XB_TMO])) break; if (_sp > XB_SPIN_CAP) { atomicAdd(&(bar)[XB_TMO], 1u); break; } } } } while (0)
; DI void xcd_barrier(const XcdBarrier& b) {
;     ...
;         const unsigned old = xb_add(&bar[XB_XSUB(b.x)], 1u);
;         const unsigned gen = old / nloc;
;         if (old + 1u == (gen + 1u) * nloc) {
;             __builtin_amdgcn_fence(__ATOMIC_RELEASE, "agent");
;             asm volatile("s_waitcnt vmcnt(0)" ::: "memory");
;             const unsigned og = xb_add(&bar[XB_TOP], 1u);
;             const unsigned tg = og / nx;
;             if (og + 1u == (tg + 1u) * nx) xb_add(&bar[XB_TOPGEN], 1u);
;             else XB_SPIN(xb_ld(&bar[XB_TOPGEN]) == tg, bar);
.LBB0_181:
	s_or_b64 exec, exec, s[42:43]
	s_waitcnt vmcnt(0)
	v_readfirstlane_b32 s6, v3
	v_sub_u32_e32 v4, 0, v2
	v_readlane_b32 s8, v251, 2
	v_add_u32_e32 v3, s6, v0
	v_cvt_f32_u32_e32 v0, v2
	v_readlane_b32 s9, v251, 3
	s_mov_b64 s[42:43], -1
	v_rcp_iflag_f32_e32 v0, v0
	s_nop 0
	v_mul_f32_e32 v0, 0x4f7ffffe, v0
	v_cvt_u32_f32_e32 v0, v0
	v_mul_lo_u32 v4, v4, v0
	v_mul_hi_u32 v4, v0, v4
	v_add_u32_e32 v0, v0, v4
	v_mul_hi_u32 v0, v3, v0
	v_mul_lo_u32 v4, v0, v2
	v_sub_u32_e32 v4, v3, v4
	v_cmp_ge_u32_e32 vcc, v4, v2
	v_add_u32_e32 v5, 1, v0
	v_add_u32_e32 v3, 1, v3
	v_cndmask_b32_e32 v0, v0, v5, vcc
	v_sub_u32_e32 v5, v4, v2
	v_cndmask_b32_e32 v4, v4, v5, vcc
	v_cmp_ge_u32_e32 vcc, v4, v2
	v_add_u32_e32 v4, 1, v0
	s_nop 0
	v_cndmask_b32_e32 v0, v0, v4, vcc
	v_mul_lo_u32 v4, v2, v0
	v_add_u32_e32 v5, 1, v4
	v_cmp_eq_u32_e32 vcc, v3, v5
	s_cbranch_vccz .Lxb_notfirst_0
	buffer_wbl2 sc1
.Lxb_notfirst_0:
	v_add_u32_e32 v2, v4, v2
	v_cmp_ne_u32_e32 vcc, v3, v2
	v_mov_b64_e32 v[2:3], s[8:9]
	s_and_saveexec_b64 s[40:41], vcc
	s_cbranch_execz .LBB0_193
	v_readlane_b32 s8, v251, 2
	v_readlane_b32 s9, v251, 3
	s_mov_b64 s[46:47], 0
	s_nop 3
	global_load_dword v2, v1, s[8:9] sc1
	s_waitcnt vmcnt(0)
	v_cmp_eq_u32_e32 vcc, v2, v0
	s_and_saveexec_b64 s[42:43], vcc
	s_cbranch_execz .LBB0_192
	s_mov_b32 s6, 1
	s_branch .LBB0_185

; DI unsigned xb_ld(unsigned* p)              { return __hip_atomic_load(p, __ATOMIC_RELAXED, __HIP_MEMORY_SCOPE_AGENT); }
; DI unsigned xb_add(unsigned* p, unsigned v) { return __hip_atomic_fetch_add(p, v, __ATOMIC_RELAXED, __HIP_MEMORY_SCOPE_AGENT); }
; #define XB_SPIN(cond, bar) do { unsigned _sp = 0; while (cond) { __builtin_amdgcn_s_sleep(1); \
;     if ((++_sp & 255u) == 0u) { if (xb_ld(&(bar)[XB_TMO])) break; if (_sp > XB_SPIN_CAP) { atomicAdd(&(bar)[XB_TMO], 1u); break; } } } } while (0)
; DI void xcd_barrier(const XcdBarrier& b) {
;     ...
;         const unsigned old = xb_add(&bar[XB_XSUB(b.x)], 1u);
;         const unsigned gen = old / nloc;
;         if (old + 1u == (gen + 1u) * nloc) {
;             __builtin_amdgcn_fence(__ATOMIC_RELEASE, "agent");
;             asm volatile("s_waitcnt vmcnt(0)" ::: "memory");
;             const unsigned og = xb_add(&bar[XB_TOP], 1u);
;             const unsigned tg = og / nx;
;             if (og + 1u == (tg + 1u) * nx) xb_add(&bar[XB_TOPGEN], 1u);
;             else XB_SPIN(xb_ld(&bar[XB_TOPGEN]) == tg, bar);
.LBB0_352:
	s_or_b64 exec, exec, s[40:41]
	s_waitcnt vmcnt(0)
	v_readfirstlane_b32 s6, v3
	v_sub_u32_e32 v4, 0, v2
	v_readlane_b32 s12, v251, 2
	v_add_u32_e32 v3, s6, v0
	v_cvt_f32_u32_e32 v0, v2
	v_readlane_b32 s13, v251, 3
	s_mov_b64 s[40:41], -1
	v_rcp_iflag_f32_e32 v0, v0
	s_nop 0
	v_mul_f32_e32 v0, 0x4f7ffffe, v0
	v_cvt_u32_f32_e32 v0, v0
	v_mul_lo_u32 v4, v4, v0
	v_mul_hi_u32 v4, v0, v4
	v_add_u32_e32 v0, v0, v4
	v_mul_hi_u32 v0, v3, v0
	v_mul_lo_u32 v4, v0, v2
	v_sub_u32_e32 v4, v3, v4
	v_cmp_ge_u32_e32 vcc, v4, v2
	v_add_u32_e32 v5, 1, v0
	v_add_u32_e32 v3, 1, v3
	v_cndmask_b32_e32 v0, v0, v5, vcc
	v_sub_u32_e32 v5, v4, v2
	v_cndmask_b32_e32 v4, v4, v5, vcc
	v_cmp_ge_u32_e32 vcc, v4, v2
	v_add_u32_e32 v4, 1, v0
	s_nop 0
	v_cndmask_b32_e32 v0, v0, v4, vcc
	v_mul_lo_u32 v4, v2, v0
	v_add_u32_e32 v5, 1, v4
	v_cmp_eq_u32_e32 vcc, v3, v5
	s_cbranch_vccz .Lxb_notfirst_1
	buffer_wbl2 sc1
.Lxb_notfirst_1:
	v_add_u32_e32 v2, v4, v2
	v_cmp_ne_u32_e32 vcc, v3, v2
	v_mov_b64_e32 v[2:3], s[12:13]
	s_and_saveexec_b64 s[12:13], vcc
	s_cbranch_execz .LBB0_364
	v_readlane_b32 s18, v251, 2
	v_readlane_b32 s19, v251, 3
	s_mov_b64 s[42:43], 0
	s_nop 3
	global_load_dword v2, v1, s[18:19] sc1
	s_waitcnt vmcnt(0)
	v_cmp_eq_u32_e32 vcc, v2, v0
	s_and_saveexec_b64 s[40:41], vcc
	s_cbranch_execz .LBB0_363
	s_mov_b32 s6, 1
	s_branch .LBB0_356

; DI unsigned xb_ld(unsigned* p)              { return __hip_atomic_load(p, __ATOMIC_RELAXED, __HIP_MEMORY_SCOPE_AGENT); }
; DI unsigned xb_add(unsigned* p, unsigned v) { return __hip_atomic_fetch_add(p, v, __ATOMIC_RELAXED, __HIP_MEMORY_SCOPE_AGENT); }
; #define XB_SPIN(cond, bar) do { unsigned _sp = 0; while (cond) { __builtin_amdgcn_s_sleep(1); \
;     if ((++_sp & 255u) == 0u) { if (xb_ld(&(bar)[XB_TMO])) break; if (_sp > XB_SPIN_CAP) { atomicAdd(&(bar)[XB_TMO], 1u); break; } } } } while (0)
; DI void xcd_barrier(const XcdBarrier& b) {
;     ...
;         const unsigned old = xb_add(&bar[XB_XSUB(b.x)], 1u);
;         const unsigned gen = old / nloc;
;         if (old + 1u == (gen + 1u) * nloc) {
;             __builtin_amdgcn_fence(__ATOMIC_RELEASE, "agent");
;             asm volatile("s_waitcnt vmcnt(0)" ::: "memory");
;             const unsigned og = xb_add(&bar[XB_TOP], 1u);
;             const unsigned tg = og / nx;
;             if (og + 1u == (tg + 1u) * nx) xb_add(&bar[XB_TOPGEN], 1u);
;             else XB_SPIN(xb_ld(&bar[XB_TOPGEN]) == tg, bar);
.Lxb_notfirst_2:
	v_add_u32_e32 v2, v4, v2
	v_cmp_ne_u32_e32 vcc, v3, v2
	v_mov_b64_e32 v[2:3], s[8:9]
	s_and_saveexec_b64 s[40:41], vcc
	s_cbranch_execz .LBB0_551
	v_readlane_b32 s8, v251, 2
	v_readlane_b32 s9, v251, 3
	s_mov_b64 s[44:45], 0
	s_nop 3
	global_load_dword v2, v1, s[8:9] sc1
	s_waitcnt vmcnt(0)
	v_cmp_eq_u32_e32 vcc, v2, v0
	s_and_saveexec_b64 s[42:43], vcc
	s_cbranch_execz .LBB0_550
	s_mov_b32 s6, 1
	s_branch .LBB0_543
